# qkprep: xor-1/2/4/8 butterfly steps of the wave sums as DPP adds and xor-32 as permlane32_swap instead of ds_bpermute (on top of the 5-slot PROJ ring)
# baseline (speedup 1.0000x reference)
.LBB0_794:
	s_or_b64 exec, exec, s[12:13]
	v_add_co_u32_e32 v18, vcc, 0x2801000, v60
	v_mul_hi_i32 v0, v46, s55
	s_nop 0
	v_addc_co_u32_e32 v19, vcc, 0, v61, vcc
	v_mov_b32_e32 v22, v102
	v_mov_b32_e32 v23, v103
	v_mov_b32_e32 v24, v104
	v_mov_b32_e32 v25, v105
	v_lshrrev_b32_e32 v18, 31, v0
	v_ashrrev_i32_e32 v0, 9, v0
	v_add_u32_e32 v0, v0, v18
	v_mul_i32_i24_e32 v0, 0x900, v0
	v_sub_u32_e32 v47, v46, v0
	v_max_i32_e32 v0, 0x100, v47
	v_lshl_add_u32 v0, v0, 5, v217
	v_lshlrev_b64 v[26:27], 2, v[0:1]
	v_lshl_add_u64 v[30:31], v[48:49], 0, v[26:27]
	v_lshl_add_u64 v[32:33], v[50:51], 0, v[26:27]
	v_mov_b32_e32 v18, v106
	v_mov_b32_e32 v19, v107
	v_mov_b32_e32 v20, v108
	v_mov_b32_e32 v21, v109
	s_nop 0
	v_lshlrev_b32_e32 v62, 16, v22
	v_and_b32_e32 v63, 0xffff0000, v22
	v_lshlrev_b32_e32 v64, 16, v23
	v_and_b32_e32 v65, 0xffff0000, v23
	v_lshlrev_b32_e32 v66, 16, v24
	v_and_b32_e32 v67, 0xffff0000, v24
	v_lshlrev_b32_e32 v68, 16, v25
	v_and_b32_e32 v69, 0xffff0000, v25
	v_add_f32_e32 v0, v62, v63
	v_add_f32_e32 v22, v64, v65
	v_add_f32_e32 v23, v66, v67
	v_add_f32_e32 v24, v68, v69
	v_add_f32_e32 v0, v0, v22
	v_add_f32_e32 v22, v23, v24
	v_add_f32_e32 v0, v0, v22
	s_nop 1
	v_add_f32_dpp v0, v0, v0 quad_perm:[1,0,3,2] row_mask:0xf bank_mask:0xf
	s_waitcnt lgkmcnt(0)
	s_nop 0
	v_mov_b32_e32 v26, v110
	v_mov_b32_e32 v27, v111
	v_mov_b32_e32 v28, v112
	v_mov_b32_e32 v29, v113
	v_mov_b32_e32 v22, v114
	v_mov_b32_e32 v23, v115
	v_mov_b32_e32 v24, v116
	v_mov_b32_e32 v25, v117
	s_nop 0
	v_mov_b32_e32 v30, v118
	v_mov_b32_e32 v31, v119
	v_mov_b32_e32 v32, v120
	v_mov_b32_e32 v33, v121
	v_add_u32_e32 v126, s18, v46
	s_nop 0
	v_readfirstlane_b32 s12, v126
	s_cmp_gt_i32 s12, 0x47ff
	s_cbranch_scc1 .Lqk_skip_n
	v_lshl_add_u64 v[128:129], v[54:55], 0, s[26:27]
	v_lshl_add_u64 v[128:129], s[16:17], 0, v[128:129]
	s_mov_b64 s[12:13], 0x2800000
	v_lshl_add_u64 v[88:89], v[128:129], 0, s[12:13]
	global_load_dwordx4 v[90:93], v[88:89], off
	global_load_dwordx4 v[94:97], v[88:89], off offset:1536
	s_mov_b64 s[12:13], 0x2801000
	v_lshl_add_u64 v[88:89], v[128:129], 0, s[12:13]
	global_load_dwordx4 v[102:105], v[88:89], off
	v_lshl_add_u64 v[128:129], v[56:57], 0, s[26:27]
	v_lshl_add_u64 v[128:129], s[16:17], 0, v[128:129]
	v_mov_b32_e32 v98, 0
	v_mov_b32_e32 v99, 0
	v_mov_b32_e32 v100, 0
	v_mov_b32_e32 v101, 0
	s_and_saveexec_b64 s[12:13], s[8:9]
	global_load_dwordx4 v[98:101], v[128:129], off
	s_or_b64 exec, exec, s[12:13]
	v_mul_hi_i32 v127, v126, s55
	v_lshrrev_b32_e32 v128, 31, v127
	v_ashrrev_i32_e32 v127, 9, v127
	v_add_u32_e32 v127, v127, v128
	v_mul_i32_i24_e32 v127, 0x900, v127
	v_sub_u32_e32 v127, v126, v127
	v_max_i32_e32 v127, 0x100, v127
	v_lshl_add_u32 v128, v127, 5, v217
	v_mov_b32_e32 v129, 0
	v_lshlrev_b64 v[128:129], 2, v[128:129]
	v_lshl_add_u64 v[88:89], v[48:49], 0, v[128:129]
	v_lshl_add_u64 v[128:129], v[50:51], 0, v[128:129]
	global_load_dwordx4 v[106:109], v[88:89], off
	global_load_dwordx4 v[110:113], v[128:129], off offset:16
	global_load_dwordx4 v[114:117], v[88:89], off offset:16
	global_load_dwordx4 v[118:121], v[128:129], off
.Lqk_skip_n:
	s_nop 1
	v_add_f32_dpp v0, v0, v0 quad_perm:[2,3,0,1] row_mask:0xf bank_mask:0xf
	s_waitcnt lgkmcnt(0)
	s_nop 0
	s_nop 1
	v_add_f32_dpp v0, v0, v0 row_half_mirror row_mask:0xf bank_mask:0xf
	s_waitcnt lgkmcnt(0)
	s_nop 0
	s_nop 1
	v_add_f32_dpp v0, v0, v0 row_mirror row_mask:0xf bank_mask:0xf
	s_waitcnt lgkmcnt(0)
	s_nop 0
	ds_bpermute_b32 v70, v80, v0
	s_waitcnt lgkmcnt(0)
	v_add_f32_e32 v0, v0, v70
	v_mov_b32_e32 v70, v0
	s_nop 1
	v_permlane32_swap_b32_e32 v0, v70
	s_waitcnt lgkmcnt(0)
	v_add_f32_e32 v0, v0, v70
	v_fmac_f32_e32 v63, 0xbb000000, v0
	v_fmac_f32_e32 v65, 0xbb000000, v0
	v_fmac_f32_e32 v67, 0xbb000000, v0
	v_fmac_f32_e32 v69, 0xbb000000, v0
	v_fmac_f32_e32 v62, 0xbb000000, v0
	v_fmac_f32_e32 v64, 0xbb000000, v0
	v_fmac_f32_e32 v66, 0xbb000000, v0
	v_fmac_f32_e32 v68, 0xbb000000, v0
	v_mul_f32_e32 v63, v63, v63
	v_mul_f32_e32 v65, v65, v65
	v_mul_f32_e32 v67, v67, v67
	v_mul_f32_e32 v69, v69, v69
	v_fmac_f32_e32 v63, v62, v62
	v_fmac_f32_e32 v65, v64, v64
	v_fmac_f32_e32 v67, v66, v66
	v_fmac_f32_e32 v69, v68, v68
	v_add_f32_e32 v62, v63, v65
	v_add_f32_e32 v63, v67, v69
	v_add_f32_e32 v62, v62, v63
	s_nop 1
	v_add_f32_dpp v62, v62, v62 quad_perm:[1,0,3,2] row_mask:0xf bank_mask:0xf
	s_waitcnt lgkmcnt(0)
	s_nop 0
	s_nop 1
	v_add_f32_dpp v62, v62, v62 quad_perm:[2,3,0,1] row_mask:0xf bank_mask:0xf
	s_waitcnt lgkmcnt(0)
	s_nop 0
	s_nop 1
	v_add_f32_dpp v62, v62, v62 row_half_mirror row_mask:0xf bank_mask:0xf
	s_waitcnt lgkmcnt(0)
	s_nop 0
	s_nop 1
	v_add_f32_dpp v62, v62, v62 row_mirror row_mask:0xf bank_mask:0xf
	s_waitcnt lgkmcnt(0)
	s_nop 0
	ds_bpermute_b32 v63, v80, v62
	s_waitcnt lgkmcnt(0)
	v_add_f32_e32 v62, v62, v63
	ds_bpermute_b32 v63, v81, v62
	s_and_saveexec_b64 s[12:13], s[10:11]
	s_cbranch_execz .LBB0_796
	s_waitcnt lgkmcnt(0)
	v_add_f32_e32 v62, v62, v63
	v_fmamk_f32 v62, v62, 0x3b000000, v216
	v_mul_f32_e32 v63, 0x4b800000, v62
	v_cmp_gt_f32_e32 vcc, s33, v62
	v_lshl_add_u64 v[64:65], s[16:17], 0, v[52:53]
	s_nop 0
	v_cndmask_b32_e32 v62, v62, v63, vcc
	v_rsq_f32_e32 v63, v62
	v_mul_f32_e32 v62, 0x3b000000, v0
	v_mul_f32_e32 v0, 0x45800000, v63
	v_cndmask_b32_e32 v63, v63, v0, vcc
	v_add_co_u32_e32 v64, vcc, 0x40000, v64
	s_nop 1
	v_addc_co_u32_e32 v65, vcc, 0, v65, vcc
	global_store_dwordx2 v[64:65], v[62:63], off
.LBB0_796:
	s_or_b64 exec, exec, s[12:13]
	v_lshlrev_b32_e32 v62, 16, v42
	s_waitcnt lgkmcnt(0)
	v_and_b32_e32 v63, 0xffff0000, v42
	v_pk_mul_f32 v[64:65], v[62:63], v[62:63]
	v_lshlrev_b32_e32 v66, 16, v43
	v_and_b32_e32 v67, 0xffff0000, v43
	v_pk_mul_f32 v[42:43], v[66:67], v[66:67]
	v_add_f32_e32 v0, v64, v65
	v_lshlrev_b32_e32 v68, 16, v44
	v_and_b32_e32 v69, 0xffff0000, v44
	v_add_f32_e32 v0, v42, v0
	v_pk_mul_f32 v[70:71], v[68:69], v[68:69]
	v_add_f32_e32 v0, v43, v0
	v_lshlrev_b32_e32 v72, 16, v45
	v_and_b32_e32 v73, 0xffff0000, v45
	v_add_f32_e32 v0, v70, v0
	v_pk_mul_f32 v[44:45], v[72:73], v[72:73]
	v_add_f32_e32 v0, v71, v0
	v_add_f32_e32 v0, v44, v0
	v_add_f32_e32 v0, v45, v0
	s_nop 1
	v_add_f32_dpp v0, v0, v0 quad_perm:[1,0,3,2] row_mask:0xf bank_mask:0xf
	v_cmp_lt_i32_e32 vcc, s54, v47
	s_waitcnt lgkmcnt(0)
	s_nop 0
	s_nop 1
	v_add_f32_dpp v0, v0, v0 quad_perm:[2,3,0,1] row_mask:0xf bank_mask:0xf
	s_waitcnt lgkmcnt(0)
	s_nop 0
	s_nop 1
	v_add_f32_dpp v0, v0, v0 row_half_mirror row_mask:0xf bank_mask:0xf
	s_waitcnt lgkmcnt(0)
	s_nop 0
	v_fmamk_f32 v0, v0, 0x3c800000, v216
	v_cmp_gt_f32_e64 s[12:13], s33, v0
	v_mul_f32_e32 v42, 0x4b800000, v0
	s_nop 0
	v_cndmask_b32_e64 v0, v0, v42, s[12:13]
	v_rsq_f32_e32 v0, v0
	s_nop 0
	v_mul_f32_e32 v42, 0x45800000, v0
	v_cndmask_b32_e64 v0, v0, v42, s[12:13]
	v_pk_mul_f32 v[42:43], v[14:15], v[0:1] op_sel_hi:[1,0]
	v_pk_mul_f32 v[44:45], v[16:17], v[0:1] op_sel_hi:[1,0]
	v_pk_mul_f32 v[42:43], v[42:43], v[62:63]
	v_pk_mul_f32 v[62:63], v[10:11], v[0:1] op_sel_hi:[1,0]
	v_pk_mul_f32 v[44:45], v[44:45], v[66:67]
	v_pk_mul_f32 v[64:65], v[62:63], v[68:69]
	v_pk_mul_f32 v[62:63], v[12:13], v[0:1] op_sel_hi:[1,0]
	s_nop 0
	v_pk_mul_f32 v[62:63], v[62:63], v[72:73]
	s_and_saveexec_b64 s[12:13], vcc
	s_cbranch_execz .LBB0_798
	ds_bpermute_b32 v66, v78, v42
	ds_bpermute_b32 v67, v78, v43
	ds_bpermute_b32 v68, v78, v44
	ds_bpermute_b32 v69, v78, v45
	ds_bpermute_b32 v70, v78, v64
	ds_bpermute_b32 v71, v78, v65
	ds_bpermute_b32 v72, v78, v62
	ds_bpermute_b32 v73, v78, v63
	s_waitcnt lgkmcnt(6)
	v_pk_mul_f32 v[66:67], v[30:31], v[66:67]
	s_waitcnt lgkmcnt(4)
	v_pk_mul_f32 v[68:69], v[32:33], v[68:69]
	s_waitcnt lgkmcnt(2)
	v_pk_mul_f32 v[70:71], v[26:27], v[70:71]
	v_cndmask_b32_e64 v67, v67, -v67, s[4:5]
	s_waitcnt lgkmcnt(0)
	v_pk_mul_f32 v[72:73], v[28:29], v[72:73]
	v_cndmask_b32_e64 v66, v66, -v66, s[4:5]
	v_cndmask_b32_e64 v69, v69, -v69, s[4:5]
	v_cndmask_b32_e64 v68, v68, -v68, s[4:5]
	v_cndmask_b32_e64 v71, v71, -v71, s[4:5]
	v_cndmask_b32_e64 v70, v70, -v70, s[4:5]
	v_cndmask_b32_e64 v72, v72, -v72, s[4:5]
	v_cndmask_b32_e64 v73, v73, -v73, s[4:5]
	v_pk_fma_f32 v[62:63], v[24:25], v[62:63], v[72:73]
	v_pk_fma_f32 v[64:65], v[22:23], v[64:65], v[70:71]
	v_pk_fma_f32 v[44:45], v[20:21], v[44:45], v[68:69]
	v_pk_fma_f32 v[42:43], v[18:19], v[42:43], v[66:67]
